# FoX bound scan (64 q / 64 k gains) done as one lane-parallel load + cross-lane max instead of 8 serial round trips, on top of the head-GEMM K-loop drain removal
# baseline (speedup 1.0000x reference)
.LBB0_817:
	v_and_b32_e32 v2, 63, v202
	v_cmp_gt_u32_e32 vcc, 16, v2
	v_lshlrev_b32_e32 v2, 4, v2
	s_and_saveexec_b64 s[2:3], vcc
	s_waitcnt lgkmcnt(0)
	global_load_dwordx4 v[4:7], v2, s[18:19]
	global_load_dwordx4 v[8:11], v2, s[14:15]
	s_waitcnt vmcnt(0)
	v_max3_f32 v1, |v4|, |v5|, |v6|
	v_max3_f32 v0, |v8|, |v9|, |v10|
	v_max_f32_e64 v1, v1, |v7|
	v_max_f32_e64 v0, v0, |v11|
	s_or_b64 exec, exec, s[2:3]
	s_nop 1
	v_readlane_b32 s2, v1, 0
	v_readlane_b32 s3, v0, 0
	v_readlane_b32 s0, v1, 1
	s_max_u32 s2, s2, s0
	v_readlane_b32 s1, v0, 1
	s_max_u32 s3, s3, s1
	v_readlane_b32 s0, v1, 2
	s_max_u32 s2, s2, s0
	v_readlane_b32 s1, v0, 2
	s_max_u32 s3, s3, s1
	v_readlane_b32 s0, v1, 3
	s_max_u32 s2, s2, s0
	v_readlane_b32 s1, v0, 3
	s_max_u32 s3, s3, s1
	v_readlane_b32 s0, v1, 4
	s_max_u32 s2, s2, s0
	v_readlane_b32 s1, v0, 4
	s_max_u32 s3, s3, s1
	v_readlane_b32 s0, v1, 5
	s_max_u32 s2, s2, s0
	v_readlane_b32 s1, v0, 5
	s_max_u32 s3, s3, s1
	v_readlane_b32 s0, v1, 6
	s_max_u32 s2, s2, s0
	v_readlane_b32 s1, v0, 6
	s_max_u32 s3, s3, s1
	v_readlane_b32 s0, v1, 7
	s_max_u32 s2, s2, s0
	v_readlane_b32 s1, v0, 7
	s_max_u32 s3, s3, s1
	v_readlane_b32 s0, v1, 8
	s_max_u32 s2, s2, s0
	v_readlane_b32 s1, v0, 8
	s_max_u32 s3, s3, s1
	v_readlane_b32 s0, v1, 9
	s_max_u32 s2, s2, s0
	v_readlane_b32 s1, v0, 9
	s_max_u32 s3, s3, s1
	v_readlane_b32 s0, v1, 10
	s_max_u32 s2, s2, s0
	v_readlane_b32 s1, v0, 10
	s_max_u32 s3, s3, s1
	v_readlane_b32 s0, v1, 11
	s_max_u32 s2, s2, s0
	v_readlane_b32 s1, v0, 11
	s_max_u32 s3, s3, s1
	v_readlane_b32 s0, v1, 12
	s_max_u32 s2, s2, s0
	v_readlane_b32 s1, v0, 12
	s_max_u32 s3, s3, s1
	v_readlane_b32 s0, v1, 13
	s_max_u32 s2, s2, s0
	v_readlane_b32 s1, v0, 13
	s_max_u32 s3, s3, s1
	v_readlane_b32 s0, v1, 14
	s_max_u32 s2, s2, s0
	v_readlane_b32 s1, v0, 14
	s_max_u32 s3, s3, s1
	v_readlane_b32 s0, v1, 15
	s_max_u32 s2, s2, s0
	v_readlane_b32 s1, v0, 15
	s_max_u32 s3, s3, s1
	v_mov_b32_e32 v1, s2
	v_mov_b32_e32 v0, s3
	v_readlane_b32 s0, v251, 49
	v_readlane_b32 s1, v251, 50
	s_andn2_b64 vcc, exec, s[0:1]
	v_readlane_b32 s10, v254, 48
	v_readlane_b32 s11, v254, 49
	s_cbranch_vccnz .LBB0_1037
	v_mul_f32_e32 v1, 0x4138aa3b, v1
	v_mul_f32_e32 v0, v1, v0
	s_mov_b32 s0, 0x3f83d70a
	v_fma_f32 v0, v0, s0, 0.5
	s_mov_b32 s0, 0x42700000
	v_cmp_ngt_f32_e64 s[38:39], s0, v0
	s_movk_i32 s0, 0x400
	v_cmp_gt_i32_e64 s[0:1], s0, v202
	v_ashrrev_i32_e32 v203, 31, v202
	v_fmaak_f32 v210, 2.0, v0, 0x43200000
	v_writelane_b32 v254, s0, 63
	v_writelane_b32 v254, s38, 52
	v_add_u32_e32 v211, 0xfffffe00, v202
	v_writelane_b32 v255, s1, 0
	v_readlane_b32 s0, v253, 46
	v_readlane_b32 s1, v253, 47
	v_writelane_b32 v254, s39, 53
	s_nop 0
	v_lshl_add_u64 v[188:189], v[202:203], 4, s[0:1]
	v_readlane_b32 s0, v253, 48
	s_nop 1
	v_lshl_add_u32 v212, v202, 4, s0
	v_readlane_b32 s0, v253, 42
	s_mov_b32 s6, s0
	v_readlane_b32 s1, v253, 43
	s_branch .LBB0_821
